# two-level grid barrier (8 group counters + flags in unused projA columns) replaces cg grid.sync after first sync
# speedup vs baseline: 1.1360x; 1.1360x over previous
; __global__ void __launch_bounds__(256, 2) mega(Params p, int ph_lo, int ph_hi) {
;   __shared__ __attribute__((aligned(16))) char smem[SMEM_BYTES];
;   cg::grid_group grid = cg::this_grid();
;   for (int ph = ph_lo; ph < ph_hi; ++ph) {
_Z4mega6Paramsii:
	s_mov_b32 s100, 0
	s_mov_b32 s101, s2
	s_load_dwordx2 s[4:5], s[0:1], 0x1b0
	s_waitcnt lgkmcnt(0)
	v_writelane_b32 v250, s4, 0
	s_nop 1
	v_writelane_b32 v250, s5, 1
	s_cmp_ge_i32 s4, s5
	s_cbranch_scc0 .LBB0_1
	s_getpc_b64 s[98:99]

; __global__ void __launch_bounds__(256, 2) mega(Params p, int ph_lo, int ph_hi) {
;     ...
;     if (ph + 1 < ph_hi && s != 5) grid.sync();
.LBB0_2500:
	s_waitcnt vmcnt(0)
	s_barrier
	s_mov_b64 s[2:3], exec
	v_readlane_b32 s4, v252, 27
	v_readlane_b32 s5, v252, 28
	s_and_b64 s[4:5], s[2:3], s[4:5]
	s_mov_b64 exec, s[4:5]
	s_cbranch_execnz .LBB0_2501
	s_getpc_b64 s[98:99]

; __global__ void __launch_bounds__(256, 2) mega(Params p, int ph_lo, int ph_hi) {
;     ...
;     if (ph + 1 < ph_hi && s != 5) grid.sync();
.LBB0_2501:
	v_readlane_b32 s4, v250, 54
	v_readlane_b32 s5, v250, 55
	s_cmp_lg_u32 s100, 0
	s_cbranch_scc1 .Lgs_fast
	s_sub_u32 s6, s4, 0xc8
	s_subb_u32 s7, s5, 0
	s_load_dword s8, s[4:5], 0x0
	s_load_dwordx2 s[6:7], s[6:7], 0x0
	s_waitcnt lgkmcnt(0)
	s_cmpk_lg_u32 s8, 0x200
	s_cbranch_scc1 .Lgs_slow
	s_mov_b32 s100, 1
	s_cmp_lg_u32 s101, 0
	s_cbranch_scc1 .Lgs_slow
	v_mov_b32_e32 v2, 0
	s_sub_u32 s6, s6, 0x280
	s_subb_u32 s7, s7, 0
	global_store_dword v2, v2, s[6:7] sc0 sc1
	s_sub_u32 s6, s6, 0xd00
	s_subb_u32 s7, s7, 0
	global_store_dword v2, v2, s[6:7] sc0 sc1
	s_sub_u32 s6, s6, 0xd00
	s_subb_u32 s7, s7, 0
	global_store_dword v2, v2, s[6:7] sc0 sc1
	s_sub_u32 s6, s6, 0xd00
	s_subb_u32 s7, s7, 0
	global_store_dword v2, v2, s[6:7] sc0 sc1
	s_sub_u32 s6, s6, 0xd00
	s_subb_u32 s7, s7, 0
	global_store_dword v2, v2, s[6:7] sc0 sc1
	s_sub_u32 s6, s6, 0xd00
	s_subb_u32 s7, s7, 0
	global_store_dword v2, v2, s[6:7] sc0 sc1
	s_sub_u32 s6, s6, 0xd00
	s_subb_u32 s7, s7, 0
	global_store_dword v2, v2, s[6:7] sc0 sc1
	s_sub_u32 s6, s6, 0xd00
	s_subb_u32 s7, s7, 0
	global_store_dword v2, v2, s[6:7] sc0 sc1
	s_sub_u32 s6, s6, 0xd00
	s_subb_u32 s7, s7, 0
	global_store_dword v2, v2, s[6:7] sc0 sc1
	s_sub_u32 s6, s6, 0xd00
	s_subb_u32 s7, s7, 0
	global_store_dword v2, v2, s[6:7] sc0 sc1
	s_sub_u32 s6, s6, 0xd00
	s_subb_u32 s7, s7, 0
	global_store_dword v2, v2, s[6:7] sc0 sc1
	s_sub_u32 s6, s6, 0xd00
	s_subb_u32 s7, s7, 0
	global_store_dword v2, v2, s[6:7] sc0 sc1
	s_sub_u32 s6, s6, 0xd00
	s_subb_u32 s7, s7, 0
	global_store_dword v2, v2, s[6:7] sc0 sc1
	s_sub_u32 s6, s6, 0xd00
	s_subb_u32 s7, s7, 0
	global_store_dword v2, v2, s[6:7] sc0 sc1
	s_sub_u32 s6, s6, 0xd00
	s_subb_u32 s7, s7, 0
	global_store_dword v2, v2, s[6:7] sc0 sc1
	s_sub_u32 s6, s6, 0xd00
	s_subb_u32 s7, s7, 0
	global_store_dword v2, v2, s[6:7] sc0 sc1
	s_sub_u32 s6, s6, 0xd00
	s_subb_u32 s7, s7, 0
	global_store_dword v2, v2, s[6:7] sc0 sc1
	s_branch .Lgs_slow
.Lgs_fast:
	buffer_wbl2 sc1
	s_sub_u32 s6, s4, 0xc8
	s_subb_u32 s7, s5, 0
	s_load_dwordx2 s[6:7], s[6:7], 0x0
	v_mov_b32_e32 v2, 0
	v_mov_b32_e32 v3, 1
	s_and_b32 s8, s101, 7
	s_mul_i32 s8, s8, 0xd00
	s_addk_i32 s8, 0x280
	s_waitcnt vmcnt(0) lgkmcnt(0)
	s_sub_u32 s10, s6, s8
	s_subb_u32 s11, s7, 0
	global_atomic_add v0, v2, v3, s[10:11] sc0
	s_sub_u32 s10, s10, 0x6800
	s_subb_u32 s11, s11, 0
	s_waitcnt vmcnt(0)
	v_readfirstlane_b32 s8, v0
	s_lshr_b32 s9, s8, 6
	s_and_b32 s8, s8, 63
	s_cmp_lg_u32 s8, 63
	s_cbranch_scc1 .Lgs_poll
	s_sub_u32 s4, s6, 0xd280
	s_subb_u32 s5, s7, 0
	global_atomic_add v0, v2, v3, s[4:5] sc0
	s_waitcnt vmcnt(0)
	v_readfirstlane_b32 s8, v0
	s_and_b32 s8, s8, 7
	s_cmp_lg_u32 s8, 7
	s_cbranch_scc1 .Lgs_poll
	s_sub_u32 s4, s6, 0x6a80
	s_subb_u32 s5, s7, 0
	global_atomic_add v2, v3, s[4:5]
	s_sub_u32 s4, s4, 0xd00
	s_subb_u32 s5, s5, 0
	global_atomic_add v2, v3, s[4:5]
	s_sub_u32 s4, s4, 0xd00
	s_subb_u32 s5, s5, 0
	global_atomic_add v2, v3, s[4:5]
	s_sub_u32 s4, s4, 0xd00
	s_subb_u32 s5, s5, 0
	global_atomic_add v2, v3, s[4:5]
	s_sub_u32 s4, s4, 0xd00
	s_subb_u32 s5, s5, 0
	global_atomic_add v2, v3, s[4:5]
	s_sub_u32 s4, s4, 0xd00
	s_subb_u32 s5, s5, 0
	global_atomic_add v2, v3, s[4:5]
	s_sub_u32 s4, s4, 0xd00
	s_subb_u32 s5, s5, 0
	global_atomic_add v2, v3, s[4:5]
	s_sub_u32 s4, s4, 0xd00
	s_subb_u32 s5, s5, 0
	global_atomic_add v2, v3, s[4:5]
.Lgs_poll:
	global_load_dword v0, v2, s[10:11] sc1
	s_waitcnt vmcnt(0)
	v_readfirstlane_b32 s8, v0
	s_cmp_lg_u32 s8, s9
	s_cbranch_scc1 .Lgs_to_inv
	s_sleep 1
	s_branch .Lgs_poll
.Lgs_slow:
	buffer_wbl2 sc1
	s_waitcnt vmcnt(0)
	s_load_dwordx2 s[4:5], s[4:5], 0x58
	s_mov_b64 s[6:7], exec
	v_mbcnt_lo_u32_b32 v2, s6, 0
	v_mbcnt_hi_u32_b32 v2, s7, v2
	v_cmp_eq_u32_e32 vcc, 0, v2
	s_waitcnt lgkmcnt(0)
	global_load_dword v0, v1, s[4:5] offset:40
	s_and_saveexec_b64 s[8:9], vcc
	s_cbranch_execz .LBB0_2503
	s_bcnt1_i32_b64 s6, s[6:7]
	v_mov_b32_e32 v3, s6
	global_atomic_add v3, v1, v3, s[4:5] offset:32 sc0

; __global__ void __launch_bounds__(256, 2) mega(Params p, int ph_lo, int ph_hi) {
;     ...
;     if (ph + 1 < ph_hi && s != 5) grid.sync();
.Lgs_to_inv:
	s_getpc_b64 s[98:99]

; __global__ void __launch_bounds__(256, 2) mega(Params p, int ph_lo, int ph_hi) {
;   __shared__ __attribute__((aligned(16))) char smem[SMEM_BYTES];
	.amdhsa_kernel _Z4mega6Paramsii
		.amdhsa_group_segment_fixed_size 73728
		.amdhsa_private_segment_fixed_size 0
		.amdhsa_kernarg_size 696
		.amdhsa_user_sgpr_count 2
		.amdhsa_user_sgpr_dispatch_ptr 0
		.amdhsa_user_sgpr_queue_ptr 0
		.amdhsa_user_sgpr_kernarg_segment_ptr 1
		.amdhsa_user_sgpr_dispatch_id 0
		.amdhsa_user_sgpr_kernarg_preload_length 0
		.amdhsa_user_sgpr_kernarg_preload_offset 0
		.amdhsa_user_sgpr_private_segment_size 0
		.amdhsa_uses_dynamic_stack 0
		.amdhsa_enable_private_segment 0
		.amdhsa_system_sgpr_workgroup_id_x 1
		.amdhsa_system_sgpr_workgroup_id_y 0
		.amdhsa_system_sgpr_workgroup_id_z 0
		.amdhsa_system_sgpr_workgroup_info 0
		.amdhsa_system_vgpr_workitem_id 2
		.amdhsa_next_free_vgpr 256
		.amdhsa_next_free_sgpr 102
		.amdhsa_accum_offset 256
		.amdhsa_reserve_vcc 1
		.amdhsa_float_round_mode_32 0
		.amdhsa_float_round_mode_16_64 0
		.amdhsa_float_denorm_mode_32 3
		.amdhsa_float_denorm_mode_16_64 3
		.amdhsa_dx10_clamp 1
		.amdhsa_ieee_mode 1
		.amdhsa_fp16_overflow 0
		.amdhsa_tg_split 0
		.amdhsa_exception_fp_ieee_invalid_op 0
		.amdhsa_exception_fp_denorm_src 0
		.amdhsa_exception_fp_ieee_div_zero 0
		.amdhsa_exception_fp_ieee_overflow 0
		.amdhsa_exception_fp_ieee_underflow 0
		.amdhsa_exception_fp_ieee_inexact 0
		.amdhsa_exception_int_div_zero 0
	.end_amdhsa_kernel

; __global__ void __launch_bounds__(256, 2) mega(Params p, int ph_lo, int ph_hi) {
;   __shared__ __attribute__((aligned(16))) char smem[SMEM_BYTES];
amdhsa.kernels:
  - .agpr_count:     0
    .args:
      - .offset:         0
        .size:           432
        .value_kind:     by_value
      - .offset:         432
        .size:           4
        .value_kind:     by_value
      - .offset:         436
        .size:           4
        .value_kind:     by_value
      - .offset:         440
        .size:           4
        .value_kind:     hidden_block_count_x
      - .offset:         444
        .size:           4
        .value_kind:     hidden_block_count_y
      - .offset:         448
        .size:           4
        .value_kind:     hidden_block_count_z
      - .offset:         452
        .size:           2
        .value_kind:     hidden_group_size_x
      - .offset:         454
        .size:           2
        .value_kind:     hidden_group_size_y
      - .offset:         456
        .size:           2
        .value_kind:     hidden_group_size_z
      - .offset:         458
        .size:           2
        .value_kind:     hidden_remainder_x
      - .offset:         460
        .size:           2
        .value_kind:     hidden_remainder_y
      - .offset:         462
        .size:           2
        .value_kind:     hidden_remainder_z
      - .offset:         480
        .size:           8
        .value_kind:     hidden_global_offset_x
      - .offset:         488
        .size:           8
        .value_kind:     hidden_global_offset_y
      - .offset:         496
        .size:           8
        .value_kind:     hidden_global_offset_z
      - .offset:         504
        .size:           2
        .value_kind:     hidden_grid_dims
      - .offset:         528
        .size:           8
        .value_kind:     hidden_multigrid_sync_arg
    .group_segment_fixed_size: 73728
    .kernarg_segment_align: 8
    .kernarg_segment_size: 696
    .language:       OpenCL C
    .language_version:
      - 2
      - 0
    .max_flat_workgroup_size: 256
    .name:           _Z4mega6Paramsii
    .private_segment_fixed_size: 0
    .sgpr_count:     108
    .sgpr_spill_count: 434
    .symbol:         _Z4mega6Paramsii.kd
    .uniform_work_group_size: 1
    .uses_dynamic_stack: false
    .vgpr_count:     256
    .vgpr_spill_count: 0
    .wavefront_size: 64
